# c2 plus: removed a compiler-inserted full vmcnt(0) drain between the W_in epilogue and the next tile's K-loop (no pending load targets the zeroed registers); lets epilogue stores overlap the next tile
# speedup vs baseline: 1.0031x; 1.0031x over previous
; #define PG8_BAR __builtin_amdgcn_s_barrier()
;     ...
;         const bool has_next = S.next(ui + 1, nxt);
;         const char* nA = has_next ? (const char*)g.A + (size_t)nxt.pm * tstepA + (size_t)((nxt.pn >> g.ash) * g.amul) * 2 : cA; const char* nB = has_next ? (const char*)g.Bt + (size_t)nxt.pn * tstepB : cB;
;         PG8_KLOOP();
;         if (wr == 0) PG8_BAR;
;         E(acc, cur, wr, wc, fr, fq);
;         if (!has_next) break;
; #pragma unroll
;         for (int a = 0; a < 2; ++a)
; #pragma unroll
;             for (int b = 0; b < 2; ++b)
; #pragma unroll
;                 for (int m = 0; m < 4; ++m)
; #pragma unroll
;                     for (int n = 0; n < 2; ++n) acc[a][b][m][n] = (f32x4){0.f, 0.f, 0.f, 0.f};
;         cur = nxt; cA = nA; cB = nB; ++ui;
.LBB0_111:
	s_ashr_i32 s75, s74, 31
	s_lshl_b64 s[22:23], s[74:75], 20
	s_add_u32 s26, s2, s22
	s_addc_u32 s27, s3, s23
	s_and_b64 s[22:23], s[40:41], exec
	s_cselect_b32 s65, s27, s17
	s_cselect_b32 s75, s26, s16
	s_ashr_i32 s51, s50, 31
	s_lshl_b64 s[22:23], s[50:51], 20
	s_add_u32 s90, s25, s22
	s_addc_u32 s91, s76, s23
	s_and_b64 s[22:23], s[40:41], exec
	s_cselect_b32 s51, s91, s63
	s_cselect_b32 s89, s90, s62
	s_add_u32 vcc_lo, s16, 0x80080
	s_addc_u32 vcc_hi, s17, 0
	s_add_u32 s62, s62, 0x100
	v_mov_b32_e32 v2, 0
	s_addc_u32 s63, s63, 0
	s_mov_b32 s96, -2
	v_mov_b32_e32 v3, v2
	v_mov_b32_e32 v4, v2
	v_mov_b32_e32 v5, v2
	v_mov_b32_e32 v6, v2
	v_mov_b32_e32 v7, v2
	v_mov_b32_e32 v8, v2
	v_mov_b32_e32 v9, v2
	v_mov_b32_e32 v18, v2
	v_mov_b32_e32 v19, v2
	v_mov_b32_e32 v20, v2
	v_mov_b32_e32 v21, v2
	v_mov_b32_e32 v22, v2
	v_mov_b32_e32 v23, v2
	v_mov_b32_e32 v24, v2
	v_mov_b32_e32 v25, v2
	v_mov_b32_e32 v34, v2
	v_mov_b32_e32 v35, v2
	v_mov_b32_e32 v36, v2
	v_mov_b32_e32 v37, v2
	v_mov_b32_e32 v38, v2
	v_mov_b32_e32 v39, v2
	v_mov_b32_e32 v40, v2
	v_mov_b32_e32 v41, v2
	v_mov_b32_e32 v50, v2
	v_mov_b32_e32 v51, v2
	v_mov_b32_e32 v52, v2
	v_mov_b32_e32 v53, v2
	v_mov_b32_e32 v54, v2
	v_mov_b32_e32 v55, v2
	v_mov_b32_e32 v56, v2
	v_mov_b32_e32 v57, v2
	v_mov_b32_e32 v10, v2
	v_mov_b32_e32 v11, v2
	v_mov_b32_e32 v12, v2
	v_mov_b32_e32 v13, v2
	v_mov_b32_e32 v14, v2
	v_mov_b32_e32 v15, v2
	v_mov_b32_e32 v16, v2
	v_mov_b32_e32 v17, v2
	v_mov_b32_e32 v26, v2
	v_mov_b32_e32 v27, v2
	v_mov_b32_e32 v28, v2
	v_mov_b32_e32 v29, v2
	v_mov_b32_e32 v30, v2
	v_mov_b32_e32 v31, v2
	v_mov_b32_e32 v32, v2
	v_mov_b32_e32 v33, v2
	v_mov_b32_e32 v42, v2
	v_mov_b32_e32 v43, v2
	v_mov_b32_e32 v44, v2
	v_mov_b32_e32 v45, v2
	v_mov_b32_e32 v46, v2
	v_mov_b32_e32 v47, v2
	v_mov_b32_e32 v48, v2
	v_mov_b32_e32 v49, v2
	v_mov_b32_e32 v58, v2
	v_mov_b32_e32 v59, v2
	v_mov_b32_e32 v60, v2
	v_mov_b32_e32 v61, v2
	v_mov_b32_e32 v62, v2
	v_mov_b32_e32 v63, v2
	v_mov_b32_e32 v64, v2
	v_mov_b32_e32 v65, v2
	v_mov_b32_e32 v66, v2
	v_mov_b32_e32 v67, v2
	v_mov_b32_e32 v68, v2
	v_mov_b32_e32 v69, v2
	v_mov_b32_e32 v70, v2
	v_mov_b32_e32 v71, v2
	v_mov_b32_e32 v72, v2
	v_mov_b32_e32 v73, v2
	v_mov_b32_e32 v82, v2
	v_mov_b32_e32 v83, v2
	v_mov_b32_e32 v84, v2
	v_mov_b32_e32 v85, v2
	v_mov_b32_e32 v86, v2
	v_mov_b32_e32 v87, v2
	v_mov_b32_e32 v88, v2
	v_mov_b32_e32 v89, v2
	v_mov_b32_e32 v98, v2
	v_mov_b32_e32 v99, v2
	v_mov_b32_e32 v100, v2
	v_mov_b32_e32 v101, v2
	v_mov_b32_e32 v102, v2
	v_mov_b32_e32 v103, v2
	v_mov_b32_e32 v104, v2
	v_mov_b32_e32 v105, v2
	v_mov_b32_e32 v114, v2
	v_mov_b32_e32 v115, v2
	v_mov_b32_e32 v116, v2
	v_mov_b32_e32 v117, v2
	v_mov_b32_e32 v118, v2
	v_mov_b32_e32 v119, v2
	v_mov_b32_e32 v120, v2
	v_mov_b32_e32 v121, v2
	v_mov_b32_e32 v74, v2
	v_mov_b32_e32 v75, v2
	v_mov_b32_e32 v76, v2
	v_mov_b32_e32 v77, v2
	v_mov_b32_e32 v78, v2
	v_mov_b32_e32 v79, v2
	v_mov_b32_e32 v80, v2
	v_mov_b32_e32 v81, v2
	v_mov_b32_e32 v90, v2
	v_mov_b32_e32 v91, v2
	v_mov_b32_e32 v92, v2
	v_mov_b32_e32 v93, v2
	v_mov_b32_e32 v94, v2
	v_mov_b32_e32 v95, v2
	v_mov_b32_e32 v96, v2
	v_mov_b32_e32 v97, v2
	v_mov_b32_e32 v106, v2
	v_mov_b32_e32 v107, v2
	v_mov_b32_e32 v108, v2
	v_mov_b32_e32 v109, v2
	v_mov_b32_e32 v110, v2
	v_mov_b32_e32 v111, v2
	v_mov_b32_e32 v112, v2
	v_mov_b32_e32 v113, v2
	v_mov_b32_e32 v122, v2
	v_mov_b32_e32 v123, v2
	v_mov_b32_e32 v124, v2
	v_mov_b32_e32 v125, v2
	v_mov_b32_e32 v126, v2
	v_mov_b32_e32 v127, v2
	v_mov_b32_e32 v128, v2
	v_mov_b32_e32 v129, v2
